# ain-store write-through: v92 plus sc1 on the 4 AinG stores of rwkv_ain_phase
# speedup vs baseline: 1.0053x; 1.0053x over previous
.Lain_start:
	s_cmp_lt_u32 s72, 0x80
	s_movk_i32 s11, 0x1000
	s_cselect_b32 s11, 0x100, s11
	s_lshl_b32 s10, s72, 6
	s_add_i32 s2, s11, -1
	s_and_b32 s12, s10, s2
	s_add_i32 s13, s12, 64
	s_add_i32 s4, s10, -1
	s_mul_i32 s4, s4, 0x2180
	s_ashr_i32 s5, s4, 31
	s_add_u32 s4, s4, 0x3382000
	s_addc_u32 s5, s5, 0
	s_add_u32 s4, s4, s76
	s_addc_u32 s5, s5, s77
	v_readlane_b32 s60, v252, 26
	v_readlane_b32 s61, v252, 27
	v_and_b32_e32 v244, 31, v177
	v_lshrrev_b32_e32 v245, 5, v177
	v_cmp_gt_u32_e32 vcc, 24, v244
	s_and_saveexec_b64 s[18:19], vcc
	v_mul_u32_u24_e32 v246, 0x8600, v245
	v_lshl_add_u32 v246, v244, 4, v246
	v_lshlrev_b32_e32 v247, 5, v244
	global_load_dwordx4 v[0:3], v246, s[4:5]
	s_add_u32 s4, s4, 0x2180
	s_addc_u32 s5, s5, 0
	global_load_dwordx4 v[4:7], v246, s[4:5]
	s_add_u32 s4, s4, 0x2180
	s_addc_u32 s5, s5, 0
	global_load_dwordx4 v[8:11], v246, s[4:5]
	s_add_u32 s4, s4, 0x2180
	s_addc_u32 s5, s5, 0
	global_load_dwordx4 v[12:15], v246, s[4:5]
	s_add_u32 s4, s4, 0x2180
	s_addc_u32 s5, s5, 0
	global_load_dwordx4 v[16:19], v246, s[4:5]
	s_add_u32 s4, s4, 0x2180
	s_addc_u32 s5, s5, 0
	global_load_dwordx4 v[20:23], v246, s[4:5]
	s_add_u32 s24, s60, 0x1800
	s_addc_u32 s25, s61, 0
	global_load_dwordx4 v[192:195], v247, s[24:25]
	global_load_dwordx4 v[196:199], v247, s[24:25] offset:16
	s_add_u32 s24, s24, 0x1b00
	s_addc_u32 s25, s25, 0
	global_load_dwordx4 v[200:203], v247, s[24:25]
	global_load_dwordx4 v[204:207], v247, s[24:25] offset:16
	s_add_u32 s24, s24, 0x1b00
	s_addc_u32 s25, s25, 0
	global_load_dwordx4 v[208:211], v247, s[24:25]
	global_load_dwordx4 v[232:235], v247, s[24:25] offset:16
	v_cmp_gt_u32_e64 s[38:39], 8, v244
	v_mov_b32_e32 v248, 0xbfb8aa3b
	v_mov_b32_e32 v251, 0x4038aa3b
	v_cndmask_b32_e64 v248, v248, v251, s[38:39]
	v_cndmask_b32_e64 v249, 1.0, -2.0, s[38:39]
	v_cndmask_b32_e64 v250, 0, 1.0, s[38:39]
	v_add_u32_e32 v251, -8, v244
	v_cmp_gt_u32_e64 s[36:37], 4, v251
	v_cmp_eq_u32_e32 vcc, 0, v245
	s_cmp_eq_u32 s12, 0
	s_cselect_b64 s[30:31], vcc, 0
	v_cmp_eq_u32_e32 vcc, 15, v245
	s_cmp_eq_u32 s13, s11
	s_cselect_b64 s[40:41], vcc, 0
	s_mul_i32 s2, s72, 0x6000
	s_add_u32 s2, s2, 0xf984000
	s_add_u32 s2, s2, s76
	s_addc_u32 s3, s77, 0
	v_mul_u32_u24_e32 v246, 0x600, v245
	v_lshl_add_u32 v246, v244, 4, v246
	s_waitcnt vmcnt(0)
	v_cndmask_b32_e64 v0, v0, 0, s[30:31]
	v_cndmask_b32_e64 v1, v1, 0, s[30:31]
	v_cndmask_b32_e64 v2, v2, 0, s[30:31]
	v_cndmask_b32_e64 v3, v3, 0, s[30:31]
	v_cndmask_b32_e64 v20, v20, 0, s[40:41]
	v_cndmask_b32_e64 v21, v21, 0, s[40:41]
	v_cndmask_b32_e64 v22, v22, 0, s[40:41]
	v_cndmask_b32_e64 v23, v23, 0, s[40:41]
	v_lshlrev_b32_e32 v251, 16, v0
	v_mul_f32_e32 v236, v192, v251
	v_lshlrev_b32_e32 v251, 16, v4
	v_fmac_f32_e32 v236, v200, v251
	v_lshlrev_b32_e32 v251, 16, v8
	v_fmac_f32_e32 v236, v208, v251
	v_and_b32_e32 v251, 0xffff0000, v0
	v_mul_f32_e32 v237, v193, v251
	v_and_b32_e32 v251, 0xffff0000, v4
	v_fmac_f32_e32 v237, v201, v251
	v_and_b32_e32 v251, 0xffff0000, v8
	v_fmac_f32_e32 v237, v209, v251
	v_lshlrev_b32_e32 v251, 16, v1
	v_mul_f32_e32 v238, v194, v251
	v_lshlrev_b32_e32 v251, 16, v5
	v_fmac_f32_e32 v238, v202, v251
	v_lshlrev_b32_e32 v251, 16, v9
	v_fmac_f32_e32 v238, v210, v251
	v_and_b32_e32 v251, 0xffff0000, v1
	v_mul_f32_e32 v239, v195, v251
	v_and_b32_e32 v251, 0xffff0000, v5
	v_fmac_f32_e32 v239, v203, v251
	v_and_b32_e32 v251, 0xffff0000, v9
	v_fmac_f32_e32 v239, v211, v251
	v_lshlrev_b32_e32 v251, 16, v2
	v_mul_f32_e32 v240, v196, v251
	v_lshlrev_b32_e32 v251, 16, v6
	v_fmac_f32_e32 v240, v204, v251
	v_lshlrev_b32_e32 v251, 16, v10
	v_fmac_f32_e32 v240, v232, v251
	v_and_b32_e32 v251, 0xffff0000, v2
	v_mul_f32_e32 v241, v197, v251
	v_and_b32_e32 v251, 0xffff0000, v6
	v_fmac_f32_e32 v241, v205, v251
	v_and_b32_e32 v251, 0xffff0000, v10
	v_fmac_f32_e32 v241, v233, v251
	v_lshlrev_b32_e32 v251, 16, v3
	v_mul_f32_e32 v242, v198, v251
	v_lshlrev_b32_e32 v251, 16, v7
	v_fmac_f32_e32 v242, v206, v251
	v_lshlrev_b32_e32 v251, 16, v11
	v_fmac_f32_e32 v242, v234, v251
	v_and_b32_e32 v251, 0xffff0000, v3
	v_mul_f32_e32 v243, v199, v251
	v_and_b32_e32 v251, 0xffff0000, v7
	v_fmac_f32_e32 v243, v207, v251
	v_and_b32_e32 v251, 0xffff0000, v11
	v_fmac_f32_e32 v243, v235, v251
	v_mul_f32_e32 v251, v248, v236
	v_exp_f32_e32 v251, v251
	s_nop 0
	v_add_f32_e32 v251, 1.0, v251
	v_rcp_f32_e32 v251, v251
	s_nop 0
	v_fma_f32 v251, v251, v249, v250
	v_cndmask_b32_e64 v236, v251, v236, s[36:37]
	v_mul_f32_e32 v251, v248, v237
	v_exp_f32_e32 v251, v251
	s_nop 0
	v_add_f32_e32 v251, 1.0, v251
	v_rcp_f32_e32 v251, v251
	s_nop 0
	v_fma_f32 v251, v251, v249, v250
	v_cndmask_b32_e64 v237, v251, v237, s[36:37]
	v_mul_f32_e32 v251, v248, v238
	v_exp_f32_e32 v251, v251
	s_nop 0
	v_add_f32_e32 v251, 1.0, v251
	v_rcp_f32_e32 v251, v251
	s_nop 0
	v_fma_f32 v251, v251, v249, v250
	v_cndmask_b32_e64 v238, v251, v238, s[36:37]
	v_mul_f32_e32 v251, v248, v239
	v_exp_f32_e32 v251, v251
	s_nop 0
	v_add_f32_e32 v251, 1.0, v251
	v_rcp_f32_e32 v251, v251
	s_nop 0
	v_fma_f32 v251, v251, v249, v250
	v_cndmask_b32_e64 v239, v251, v239, s[36:37]
	v_mul_f32_e32 v251, v248, v240
	v_exp_f32_e32 v251, v251
	s_nop 0
	v_add_f32_e32 v251, 1.0, v251
	v_rcp_f32_e32 v251, v251
	s_nop 0
	v_fma_f32 v251, v251, v249, v250
	v_cndmask_b32_e64 v240, v251, v240, s[36:37]
	v_mul_f32_e32 v251, v248, v241
	v_exp_f32_e32 v251, v251
	s_nop 0
	v_add_f32_e32 v251, 1.0, v251
	v_rcp_f32_e32 v251, v251
	s_nop 0
	v_fma_f32 v251, v251, v249, v250
	v_cndmask_b32_e64 v241, v251, v241, s[36:37]
	v_mul_f32_e32 v251, v248, v242
	v_exp_f32_e32 v251, v251
	s_nop 0
	v_add_f32_e32 v251, 1.0, v251
	v_rcp_f32_e32 v251, v251
	s_nop 0
	v_fma_f32 v251, v251, v249, v250
	v_cndmask_b32_e64 v242, v251, v242, s[36:37]
	v_mul_f32_e32 v251, v248, v243
	v_exp_f32_e32 v251, v251
	s_nop 0
	v_add_f32_e32 v251, 1.0, v251
	v_rcp_f32_e32 v251, v251
	s_nop 0
	v_fma_f32 v251, v251, v249, v250
	v_cndmask_b32_e64 v243, v251, v243, s[36:37]
	v_cvt_pk_bf16_f32 v236, v236, v237
	v_cvt_pk_bf16_f32 v237, v238, v239
	v_cvt_pk_bf16_f32 v238, v240, v241
	v_cvt_pk_bf16_f32 v239, v242, v243
	global_store_dwordx4 v246, v[236:239], s[2:3] sc1
	s_nop 1
	v_lshlrev_b32_e32 v251, 16, v4
	v_mul_f32_e32 v236, v192, v251
	v_lshlrev_b32_e32 v251, 16, v8
	v_fmac_f32_e32 v236, v200, v251
	v_lshlrev_b32_e32 v251, 16, v12
	v_fmac_f32_e32 v236, v208, v251
	v_and_b32_e32 v251, 0xffff0000, v4
	v_mul_f32_e32 v237, v193, v251
	v_and_b32_e32 v251, 0xffff0000, v8
	v_fmac_f32_e32 v237, v201, v251
	v_and_b32_e32 v251, 0xffff0000, v12
	v_fmac_f32_e32 v237, v209, v251
	v_lshlrev_b32_e32 v251, 16, v5
	v_mul_f32_e32 v238, v194, v251
	v_lshlrev_b32_e32 v251, 16, v9
	v_fmac_f32_e32 v238, v202, v251
	v_lshlrev_b32_e32 v251, 16, v13
	v_fmac_f32_e32 v238, v210, v251
	v_and_b32_e32 v251, 0xffff0000, v5
	v_mul_f32_e32 v239, v195, v251
	v_and_b32_e32 v251, 0xffff0000, v9
	v_fmac_f32_e32 v239, v203, v251
	v_and_b32_e32 v251, 0xffff0000, v13
	v_fmac_f32_e32 v239, v211, v251
	v_lshlrev_b32_e32 v251, 16, v6
	v_mul_f32_e32 v240, v196, v251
	v_lshlrev_b32_e32 v251, 16, v10
	v_fmac_f32_e32 v240, v204, v251
	v_lshlrev_b32_e32 v251, 16, v14
	v_fmac_f32_e32 v240, v232, v251
	v_and_b32_e32 v251, 0xffff0000, v6
	v_mul_f32_e32 v241, v197, v251
	v_and_b32_e32 v251, 0xffff0000, v10
	v_fmac_f32_e32 v241, v205, v251
	v_and_b32_e32 v251, 0xffff0000, v14
	v_fmac_f32_e32 v241, v233, v251
	v_lshlrev_b32_e32 v251, 16, v7
	v_mul_f32_e32 v242, v198, v251
	v_lshlrev_b32_e32 v251, 16, v11
	v_fmac_f32_e32 v242, v206, v251
	v_lshlrev_b32_e32 v251, 16, v15
	v_fmac_f32_e32 v242, v234, v251
	v_and_b32_e32 v251, 0xffff0000, v7
	v_mul_f32_e32 v243, v199, v251
	v_and_b32_e32 v251, 0xffff0000, v11
	v_fmac_f32_e32 v243, v207, v251
	v_and_b32_e32 v251, 0xffff0000, v15
	v_fmac_f32_e32 v243, v235, v251
	v_mul_f32_e32 v251, v248, v236
	v_exp_f32_e32 v251, v251
	s_nop 0
	v_add_f32_e32 v251, 1.0, v251
	v_rcp_f32_e32 v251, v251
	s_nop 0
	v_fma_f32 v251, v251, v249, v250
	v_cndmask_b32_e64 v236, v251, v236, s[36:37]
	v_mul_f32_e32 v251, v248, v237
	v_exp_f32_e32 v251, v251
	s_nop 0
	v_add_f32_e32 v251, 1.0, v251
	v_rcp_f32_e32 v251, v251
	s_nop 0
	v_fma_f32 v251, v251, v249, v250
	v_cndmask_b32_e64 v237, v251, v237, s[36:37]
	v_mul_f32_e32 v251, v248, v238
	v_exp_f32_e32 v251, v251
	s_nop 0
	v_add_f32_e32 v251, 1.0, v251
	v_rcp_f32_e32 v251, v251
	s_nop 0
	v_fma_f32 v251, v251, v249, v250
	v_cndmask_b32_e64 v238, v251, v238, s[36:37]
	v_mul_f32_e32 v251, v248, v239
	v_exp_f32_e32 v251, v251
	s_nop 0
	v_add_f32_e32 v251, 1.0, v251
	v_rcp_f32_e32 v251, v251
	s_nop 0
	v_fma_f32 v251, v251, v249, v250
	v_cndmask_b32_e64 v239, v251, v239, s[36:37]
	v_mul_f32_e32 v251, v248, v240
	v_exp_f32_e32 v251, v251
	s_nop 0
	v_add_f32_e32 v251, 1.0, v251
	v_rcp_f32_e32 v251, v251
	s_nop 0
	v_fma_f32 v251, v251, v249, v250
	v_cndmask_b32_e64 v240, v251, v240, s[36:37]
	v_mul_f32_e32 v251, v248, v241
	v_exp_f32_e32 v251, v251
	s_nop 0
	v_add_f32_e32 v251, 1.0, v251
	v_rcp_f32_e32 v251, v251
	s_nop 0
	v_fma_f32 v251, v251, v249, v250
	v_cndmask_b32_e64 v241, v251, v241, s[36:37]
	v_mul_f32_e32 v251, v248, v242
	v_exp_f32_e32 v251, v251
	s_nop 0
	v_add_f32_e32 v251, 1.0, v251
	v_rcp_f32_e32 v251, v251
	s_nop 0
	v_fma_f32 v251, v251, v249, v250
	v_cndmask_b32_e64 v242, v251, v242, s[36:37]
	v_mul_f32_e32 v251, v248, v243
	v_exp_f32_e32 v251, v251
	s_nop 0
	v_add_f32_e32 v251, 1.0, v251
	v_rcp_f32_e32 v251, v251
	s_nop 0
	v_fma_f32 v251, v251, v249, v250
	v_cndmask_b32_e64 v243, v251, v243, s[36:37]
	v_cvt_pk_bf16_f32 v236, v236, v237
	v_cvt_pk_bf16_f32 v237, v238, v239
	v_cvt_pk_bf16_f32 v238, v240, v241
	v_cvt_pk_bf16_f32 v239, v242, v243
	global_store_dwordx4 v246, v[236:239], s[2:3] offset:384 sc1
	s_nop 1
	v_lshlrev_b32_e32 v251, 16, v8
	v_mul_f32_e32 v236, v192, v251
	v_lshlrev_b32_e32 v251, 16, v12
	v_fmac_f32_e32 v236, v200, v251
	v_lshlrev_b32_e32 v251, 16, v16
	v_fmac_f32_e32 v236, v208, v251
	v_and_b32_e32 v251, 0xffff0000, v8
	v_mul_f32_e32 v237, v193, v251
	v_and_b32_e32 v251, 0xffff0000, v12
	v_fmac_f32_e32 v237, v201, v251
	v_and_b32_e32 v251, 0xffff0000, v16
	v_fmac_f32_e32 v237, v209, v251
	v_lshlrev_b32_e32 v251, 16, v9
	v_mul_f32_e32 v238, v194, v251
	v_lshlrev_b32_e32 v251, 16, v13
	v_fmac_f32_e32 v238, v202, v251
	v_lshlrev_b32_e32 v251, 16, v17
	v_fmac_f32_e32 v238, v210, v251
	v_and_b32_e32 v251, 0xffff0000, v9
	v_mul_f32_e32 v239, v195, v251
	v_and_b32_e32 v251, 0xffff0000, v13
	v_fmac_f32_e32 v239, v203, v251
	v_and_b32_e32 v251, 0xffff0000, v17
	v_fmac_f32_e32 v239, v211, v251
	v_lshlrev_b32_e32 v251, 16, v10
	v_mul_f32_e32 v240, v196, v251
	v_lshlrev_b32_e32 v251, 16, v14
	v_fmac_f32_e32 v240, v204, v251
	v_lshlrev_b32_e32 v251, 16, v18
	v_fmac_f32_e32 v240, v232, v251
	v_and_b32_e32 v251, 0xffff0000, v10
	v_mul_f32_e32 v241, v197, v251
	v_and_b32_e32 v251, 0xffff0000, v14
	v_fmac_f32_e32 v241, v205, v251
	v_and_b32_e32 v251, 0xffff0000, v18
	v_fmac_f32_e32 v241, v233, v251
	v_lshlrev_b32_e32 v251, 16, v11
	v_mul_f32_e32 v242, v198, v251
	v_lshlrev_b32_e32 v251, 16, v15
	v_fmac_f32_e32 v242, v206, v251
	v_lshlrev_b32_e32 v251, 16, v19
	v_fmac_f32_e32 v242, v234, v251
	v_and_b32_e32 v251, 0xffff0000, v11
	v_mul_f32_e32 v243, v199, v251
	v_and_b32_e32 v251, 0xffff0000, v15
	v_fmac_f32_e32 v243, v207, v251
	v_and_b32_e32 v251, 0xffff0000, v19
	v_fmac_f32_e32 v243, v235, v251
	v_mul_f32_e32 v251, v248, v236
	v_exp_f32_e32 v251, v251
	s_nop 0
	v_add_f32_e32 v251, 1.0, v251
	v_rcp_f32_e32 v251, v251
	s_nop 0
	v_fma_f32 v251, v251, v249, v250
	v_cndmask_b32_e64 v236, v251, v236, s[36:37]
	v_mul_f32_e32 v251, v248, v237
	v_exp_f32_e32 v251, v251
	s_nop 0
	v_add_f32_e32 v251, 1.0, v251
	v_rcp_f32_e32 v251, v251
	s_nop 0
	v_fma_f32 v251, v251, v249, v250
	v_cndmask_b32_e64 v237, v251, v237, s[36:37]
	v_mul_f32_e32 v251, v248, v238
	v_exp_f32_e32 v251, v251
	s_nop 0
	v_add_f32_e32 v251, 1.0, v251
	v_rcp_f32_e32 v251, v251
	s_nop 0
	v_fma_f32 v251, v251, v249, v250
	v_cndmask_b32_e64 v238, v251, v238, s[36:37]
	v_mul_f32_e32 v251, v248, v239
	v_exp_f32_e32 v251, v251
	s_nop 0
	v_add_f32_e32 v251, 1.0, v251
	v_rcp_f32_e32 v251, v251
	s_nop 0
	v_fma_f32 v251, v251, v249, v250
	v_cndmask_b32_e64 v239, v251, v239, s[36:37]
	v_mul_f32_e32 v251, v248, v240
	v_exp_f32_e32 v251, v251
	s_nop 0
	v_add_f32_e32 v251, 1.0, v251
	v_rcp_f32_e32 v251, v251
	s_nop 0
	v_fma_f32 v251, v251, v249, v250
	v_cndmask_b32_e64 v240, v251, v240, s[36:37]
	v_mul_f32_e32 v251, v248, v241
	v_exp_f32_e32 v251, v251
	s_nop 0
	v_add_f32_e32 v251, 1.0, v251
	v_rcp_f32_e32 v251, v251
	s_nop 0
	v_fma_f32 v251, v251, v249, v250
	v_cndmask_b32_e64 v241, v251, v241, s[36:37]
	v_mul_f32_e32 v251, v248, v242
	v_exp_f32_e32 v251, v251
	s_nop 0
	v_add_f32_e32 v251, 1.0, v251
	v_rcp_f32_e32 v251, v251
	s_nop 0
	v_fma_f32 v251, v251, v249, v250
	v_cndmask_b32_e64 v242, v251, v242, s[36:37]
	v_mul_f32_e32 v251, v248, v243
	v_exp_f32_e32 v251, v251
	s_nop 0
	v_add_f32_e32 v251, 1.0, v251
	v_rcp_f32_e32 v251, v251
	s_nop 0
	v_fma_f32 v251, v251, v249, v250
	v_cndmask_b32_e64 v243, v251, v243, s[36:37]
	v_cvt_pk_bf16_f32 v236, v236, v237
	v_cvt_pk_bf16_f32 v237, v238, v239
	v_cvt_pk_bf16_f32 v238, v240, v241
	v_cvt_pk_bf16_f32 v239, v242, v243
	global_store_dwordx4 v246, v[236:239], s[2:3] offset:768 sc1
	s_nop 1
	v_lshlrev_b32_e32 v251, 16, v12
	v_mul_f32_e32 v236, v192, v251
	v_lshlrev_b32_e32 v251, 16, v16
	v_fmac_f32_e32 v236, v200, v251
	v_lshlrev_b32_e32 v251, 16, v20
	v_fmac_f32_e32 v236, v208, v251
	v_and_b32_e32 v251, 0xffff0000, v12
	v_mul_f32_e32 v237, v193, v251
	v_and_b32_e32 v251, 0xffff0000, v16
	v_fmac_f32_e32 v237, v201, v251
	v_and_b32_e32 v251, 0xffff0000, v20
	v_fmac_f32_e32 v237, v209, v251
	v_lshlrev_b32_e32 v251, 16, v13
	v_mul_f32_e32 v238, v194, v251
	v_lshlrev_b32_e32 v251, 16, v17
	v_fmac_f32_e32 v238, v202, v251
	v_lshlrev_b32_e32 v251, 16, v21
	v_fmac_f32_e32 v238, v210, v251
	v_and_b32_e32 v251, 0xffff0000, v13
	v_mul_f32_e32 v239, v195, v251
	v_and_b32_e32 v251, 0xffff0000, v17
	v_fmac_f32_e32 v239, v203, v251
	v_and_b32_e32 v251, 0xffff0000, v21
	v_fmac_f32_e32 v239, v211, v251
	v_lshlrev_b32_e32 v251, 16, v14
	v_mul_f32_e32 v240, v196, v251
	v_lshlrev_b32_e32 v251, 16, v18
	v_fmac_f32_e32 v240, v204, v251
	v_lshlrev_b32_e32 v251, 16, v22
	v_fmac_f32_e32 v240, v232, v251
	v_and_b32_e32 v251, 0xffff0000, v14
	v_mul_f32_e32 v241, v197, v251
	v_and_b32_e32 v251, 0xffff0000, v18
	v_fmac_f32_e32 v241, v205, v251
	v_and_b32_e32 v251, 0xffff0000, v22
	v_fmac_f32_e32 v241, v233, v251
	v_lshlrev_b32_e32 v251, 16, v15
	v_mul_f32_e32 v242, v198, v251
	v_lshlrev_b32_e32 v251, 16, v19
	v_fmac_f32_e32 v242, v206, v251
	v_lshlrev_b32_e32 v251, 16, v23
	v_fmac_f32_e32 v242, v234, v251
	v_and_b32_e32 v251, 0xffff0000, v15
	v_mul_f32_e32 v243, v199, v251
	v_and_b32_e32 v251, 0xffff0000, v19
	v_fmac_f32_e32 v243, v207, v251
	v_and_b32_e32 v251, 0xffff0000, v23
	v_fmac_f32_e32 v243, v235, v251
	v_mul_f32_e32 v251, v248, v236
	v_exp_f32_e32 v251, v251
	s_nop 0
	v_add_f32_e32 v251, 1.0, v251
	v_rcp_f32_e32 v251, v251
	s_nop 0
	v_fma_f32 v251, v251, v249, v250
	v_cndmask_b32_e64 v236, v251, v236, s[36:37]
	v_mul_f32_e32 v251, v248, v237
	v_exp_f32_e32 v251, v251
	s_nop 0
	v_add_f32_e32 v251, 1.0, v251
	v_rcp_f32_e32 v251, v251
	s_nop 0
	v_fma_f32 v251, v251, v249, v250
	v_cndmask_b32_e64 v237, v251, v237, s[36:37]
	v_mul_f32_e32 v251, v248, v238
	v_exp_f32_e32 v251, v251
	s_nop 0
	v_add_f32_e32 v251, 1.0, v251
	v_rcp_f32_e32 v251, v251
	s_nop 0
	v_fma_f32 v251, v251, v249, v250
	v_cndmask_b32_e64 v238, v251, v238, s[36:37]
	v_mul_f32_e32 v251, v248, v239
	v_exp_f32_e32 v251, v251
	s_nop 0
	v_add_f32_e32 v251, 1.0, v251
	v_rcp_f32_e32 v251, v251
	s_nop 0
	v_fma_f32 v251, v251, v249, v250
	v_cndmask_b32_e64 v239, v251, v239, s[36:37]
	v_mul_f32_e32 v251, v248, v240
	v_exp_f32_e32 v251, v251
	s_nop 0
	v_add_f32_e32 v251, 1.0, v251
	v_rcp_f32_e32 v251, v251
	s_nop 0
	v_fma_f32 v251, v251, v249, v250
	v_cndmask_b32_e64 v240, v251, v240, s[36:37]
	v_mul_f32_e32 v251, v248, v241
	v_exp_f32_e32 v251, v251
	s_nop 0
	v_add_f32_e32 v251, 1.0, v251
	v_rcp_f32_e32 v251, v251
	s_nop 0
	v_fma_f32 v251, v251, v249, v250
	v_cndmask_b32_e64 v241, v251, v241, s[36:37]
	v_mul_f32_e32 v251, v248, v242
	v_exp_f32_e32 v251, v251
	s_nop 0
	v_add_f32_e32 v251, 1.0, v251
	v_rcp_f32_e32 v251, v251
	s_nop 0
	v_fma_f32 v251, v251, v249, v250
	v_cndmask_b32_e64 v242, v251, v242, s[36:37]
	v_mul_f32_e32 v251, v248, v243
	v_exp_f32_e32 v251, v251
	s_nop 0
	v_add_f32_e32 v251, 1.0, v251
	v_rcp_f32_e32 v251, v251
	s_nop 0
	v_fma_f32 v251, v251, v249, v250
	v_cndmask_b32_e64 v243, v251, v243, s[36:37]
	v_cvt_pk_bf16_f32 v236, v236, v237
	v_cvt_pk_bf16_f32 v237, v238, v239
	v_cvt_pk_bf16_f32 v238, v240, v241
	v_cvt_pk_bf16_f32 v239, v242, v243
	global_store_dwordx4 v246, v[236:239], s[2:3] offset:1152 sc1
	s_nop 1
	s_or_b64 exec, exec, s[18:19]
